# grid barrier polls: 4 loads in flight and no s_sleep between samples
# speedup vs baseline: 1.0052x; 1.0015x over previous
; __device__ __forceinline__ unsigned xb_ld(unsigned* p)              { return __hip_atomic_load(p, __ATOMIC_RELAXED, __HIP_MEMORY_SCOPE_AGENT); }
; #define XB_SPIN(cond, bar) do { unsigned _sp = 0; while (cond) { __builtin_amdgcn_s_sleep(1); \
;     if ((++_sp & 255u) == 0u) { if (xb_ld(&(bar)[XB_TMO])) break; if (_sp > XB_SPIN_CAP) { atomicAdd(&(bar)[XB_TMO], 1u); break; } } } } while (0)
; __device__ __forceinline__ void xcd_barrier(const XcdBarrier& b) {
;     ...
;             XB_SPIN(xb_ld(&bar[XB_XGEN(b.x)]) == gen, bar);
.LBB0_804:
	s_and_b32 s34, s38, 0xff
	s_mov_b64 s[30:31], -1
	s_cmp_lg_u32 s34, 0
	s_mov_b64 s[36:37], -1
	s_nop 0
	s_cbranch_scc1 .LBB0_807
	global_load_dword v2, v1, s[20:21] sc1
	s_waitcnt vmcnt(0)
	v_cmp_eq_u32_e32 vcc, 0, v2
	s_cbranch_vccnz .LBB0_809
	s_mov_b64 s[36:37], 0
	s_mov_b64 s[34:35], -1
